# EpiRes: both halves' residual loads issued up front into dead fragment registers; ALIGN barrier after load issue (on top of cache-aware order)
# speedup vs baseline: 1.0550x; 1.0550x over previous
; #define PG8_STAGE(bufoff, gbase, voff) do { _Pragma("unroll") for (int _i = 0; _i < 2; ++_i) \
;         __builtin_amdgcn_global_load_lds((const unsigned*)((const char*)(gbase) + (voff)[_i]), (LAS unsigned*)(lds + (bufoff) + ldsw + _i * 8192), 16, 0, 0); } while (0)
; #define PG8_LDA(dst, b, h) do { _Pragma("unroll") for (int m = 0; m < 4; ++m) _Pragma("unroll") for (int k = 0; k < 2; ++k) dst[m][k] = *(const LAS bf16x8*)(lds + PG8_SA(b, h) + aoff + m * 2048 + k * 1024); } while (0)
; #define PG8_LDB(dst, b, h) do { _Pragma("unroll") for (int n = 0; n < 2; ++n) _Pragma("unroll") for (int k = 0; k < 2; ++k) dst[n][k] = *(const LAS bf16x8*)(lds + PG8_SB(b, h) + boff + n * 2048 + k * 1024); } while (0)
; #define PG8_MMA(ai, bj, At, Bt) do { __builtin_amdgcn_s_setprio(1); _Pragma("unroll") for (int m = 0; m < 4; ++m) _Pragma("unroll") for (int n = 0; n < 2; ++n) _Pragma("unroll") for (int k = 0; k < 2; ++k) \
;         acc[ai][bj][m][n] = MFMA16(Bt[n][k], At[m][k], acc[ai][bj][m][n]); __builtin_amdgcn_s_setprio(0); } while (0)
; #define PG8_WAIT_V(n) asm volatile("s_waitcnt vmcnt(" #n ")" ::: "memory")
; #define PG8_WAIT_L(n) asm volatile("s_waitcnt lgkmcnt(" #n ")" ::: "memory")
; #define PG8_BAR __builtin_amdgcn_s_barrier()
; #define PG8_SCHED __builtin_amdgcn_sched_barrier(0)
; template <class Epi>
; __device__ __forceinline__ void gemm_phase(LAS unsigned char* lds, const Gemm g, const StaticOrder& S, const Epi& E, int tid_) {
;     ...
;         for (int t = 0; t < nt; t += 2) {
;             const bool last = (t == nt - 2);
;             const char* a1 = cA + (size_t)(t + 1) * kstep;
;             const char* a2 = last ? nA : cA + (size_t)(t + 2) * kstep; const char* b2 = last ? nB : cB + (size_t)(t + 2) * kstep;
;             const char* a3 = a2 + kstep; const char* b3 = b2 + kstep;
;             PG8_LDB(B0, 0, 0); PG8_LDB(B1, 0, 1); PG8_SCHED; PG8_LDA(At, 0, 0); PG8_STAGE(PG8_SA(1, 1), a1 + hsA, voffA);
;             PG8_WAIT_V(8); PG8_WAIT_L(0); PG8_BAR; PG8_MMA(0, 0, At, B0); PG8_MMA(0, 1, At, B1); PG8_BAR; PG8_SCHED;
;             PG8_LDA(At, 0, 1); PG8_STAGE(PG8_SB(0, 0), b2, voffB); PG8_STAGE(PG8_SB(0, 1), b2 + hsB, voffB); PG8_STAGE(PG8_SA(0, 0), a2, voffA);
;             PG8_WAIT_V(8); PG8_WAIT_L(0); PG8_BAR; PG8_MMA(1, 0, At, B0); PG8_MMA(1, 1, At, B1); PG8_BAR; PG8_SCHED;
.LBB0_683:
	s_add_i32 s69, s54, 2
	s_add_u32 s70, s28, 0x80
	s_addc_u32 s55, s29, 0
	s_add_i32 s72, 0, 0x10000
	s_cmp_eq_u32 s63, s54
	s_cselect_b32 s55, s41, s55
	s_cselect_b32 s54, s40, s70
	s_cselect_b32 s71, s53, s23
	s_cselect_b32 s70, s52, s22
	s_add_i32 s73, 0, 0x14000
	v_add_u32_e32 v142, s72, v166
	v_add_u32_e32 v169, s73, v166
	ds_read_b128 v[130:133], v142
	ds_read_b128 v[134:137], v142 offset:1024
	ds_read_b128 v[138:141], v142 offset:2048
	ds_read_b128 v[142:145], v142 offset:3072
	ds_read_b128 v[146:149], v169
	ds_read_b128 v[150:153], v169 offset:1024
	ds_read_b128 v[170:173], v169 offset:2048
	ds_read_b128 v[174:177], v169 offset:3072
	v_lshl_add_u64 v[232:233], s[28:29], 0, v[162:163]
	s_add_i32 m0, s56, 0xc000
	ds_read_b128 v[178:181], v168
	ds_read_b128 v[198:201], v168 offset:1024
	ds_read_b128 v[202:205], v168 offset:2048
	ds_read_b128 v[206:209], v168 offset:3072
	ds_read_b128 v[216:219], v168 offset:4096
	ds_read_b128 v[220:223], v168 offset:5120
	ds_read_b128 v[224:227], v168 offset:6144
	ds_read_b128 v[228:231], v168 offset:7168
	global_load_lds_dwordx4 v[232:233], off
	v_lshl_add_u64 v[232:233], s[28:29], 0, v[164:165]
	s_add_i32 m0, s56, 0xe000
	s_nop 0
	global_load_lds_dwordx4 v[232:233], off
	s_waitcnt vmcnt(8)
	s_waitcnt lgkmcnt(0)
	s_barrier
	s_setprio 1
	s_waitcnt lgkmcnt(0)
	v_mfma_f32_16x16x32_bf16 v[126:129], v[130:133], v[178:181], v[126:129]
	v_mfma_f32_16x16x32_bf16 v[122:125], v[138:141], v[178:181], v[122:125]
	v_mfma_f32_16x16x32_bf16 v[110:113], v[130:133], v[202:205], v[110:113]
	v_mfma_f32_16x16x32_bf16 v[106:109], v[138:141], v[202:205], v[106:109]
	v_mfma_f32_16x16x32_bf16 v[94:97], v[130:133], v[216:219], v[94:97]
	v_mfma_f32_16x16x32_bf16 v[90:93], v[138:141], v[216:219], v[90:93]
	v_mfma_f32_16x16x32_bf16 v[76:79], v[130:133], v[224:227], v[76:79]
	v_mfma_f32_16x16x32_bf16 v[72:75], v[138:141], v[224:227], v[72:75]
	v_mfma_f32_16x16x32_bf16 v[126:129], v[134:137], v[198:201], v[126:129]
	v_mfma_f32_16x16x32_bf16 v[122:125], v[142:145], v[198:201], v[122:125]
	v_mfma_f32_16x16x32_bf16 v[110:113], v[134:137], v[206:209], v[110:113]
	v_mfma_f32_16x16x32_bf16 v[106:109], v[142:145], v[206:209], v[106:109]
	v_mfma_f32_16x16x32_bf16 v[94:97], v[134:137], v[220:223], v[94:97]
	v_mfma_f32_16x16x32_bf16 v[90:93], v[142:145], v[220:223], v[90:93]
	v_mfma_f32_16x16x32_bf16 v[76:79], v[134:137], v[228:231], v[76:79]
	v_mfma_f32_16x16x32_bf16 v[72:75], v[142:145], v[228:231], v[72:75]
	s_setprio 0
	s_setprio 1
	v_mfma_f32_16x16x32_bf16 v[118:121], v[146:149], v[178:181], v[118:121]
	v_mfma_f32_16x16x32_bf16 v[114:117], v[170:173], v[178:181], v[114:117]
	v_mfma_f32_16x16x32_bf16 v[102:105], v[146:149], v[202:205], v[102:105]
	v_mfma_f32_16x16x32_bf16 v[98:101], v[170:173], v[202:205], v[98:101]
	v_mfma_f32_16x16x32_bf16 v[86:89], v[146:149], v[216:219], v[86:89]
	v_mfma_f32_16x16x32_bf16 v[82:85], v[170:173], v[216:219], v[82:85]
	v_mfma_f32_16x16x32_bf16 v[68:71], v[146:149], v[224:227], v[68:71]
	v_mfma_f32_16x16x32_bf16 v[64:67], v[170:173], v[224:227], v[64:67]
	v_mfma_f32_16x16x32_bf16 v[118:121], v[150:153], v[198:201], v[118:121]
	v_mfma_f32_16x16x32_bf16 v[114:117], v[174:177], v[198:201], v[114:117]
	v_mfma_f32_16x16x32_bf16 v[102:105], v[150:153], v[206:209], v[102:105]
	v_mfma_f32_16x16x32_bf16 v[98:101], v[174:177], v[206:209], v[98:101]
	v_mfma_f32_16x16x32_bf16 v[86:89], v[150:153], v[220:223], v[86:89]
	v_mfma_f32_16x16x32_bf16 v[82:85], v[174:177], v[220:223], v[82:85]
	v_mfma_f32_16x16x32_bf16 v[68:71], v[150:153], v[228:231], v[68:71]
	v_mfma_f32_16x16x32_bf16 v[64:67], v[174:177], v[228:231], v[64:67]
	s_setprio 0
	s_barrier
	s_add_i32 s72, s72, s31
	v_lshl_add_u64 v[232:233], s[70:71], 0, v[156:157]
	s_mov_b32 m0, s72
	ds_read_b128 v[178:181], v168 offset:16384
	ds_read_b128 v[198:201], v168 offset:17408
	ds_read_b128 v[202:205], v168 offset:18432
	ds_read_b128 v[206:209], v168 offset:19456
	ds_read_b128 v[216:219], v168 offset:20480
	ds_read_b128 v[220:223], v168 offset:21504
	ds_read_b128 v[224:227], v168 offset:22528
	ds_read_b128 v[228:231], v168 offset:23552
	global_load_lds_dwordx4 v[232:233], off
	s_add_i32 m0, s72, 0x2000
	v_lshl_add_u64 v[234:235], s[70:71], 0, v[160:161]
	s_add_u32 s70, s70, s4
	s_addc_u32 s71, s71, 0
	s_add_i32 s72, s73, s31
	global_load_lds_dwordx4 v[234:235], off
	v_lshl_add_u64 v[236:237], s[70:71], 0, v[156:157]
	s_mov_b32 m0, s72
	v_lshl_add_u64 v[238:239], s[70:71], 0, v[160:161]
	global_load_lds_dwordx4 v[236:237], off
	s_add_i32 m0, s72, 0x2000
	v_lshl_add_u64 v[240:241], s[54:55], 0, v[154:155]
	global_load_lds_dwordx4 v[238:239], off
	s_mov_b32 m0, s56
	v_lshl_add_u64 v[242:243], s[54:55], 0, v[158:159]
	global_load_lds_dwordx4 v[240:241], off
	s_mov_b32 m0, s57
	s_nop 0
	global_load_lds_dwordx4 v[242:243], off
	s_waitcnt vmcnt(8)
	s_waitcnt lgkmcnt(0)
	s_barrier
; #define PG8_STAGE(bufoff, gbase, voff) do { _Pragma("unroll") for (int _i = 0; _i < 2; ++_i) \
;         __builtin_amdgcn_global_load_lds((const unsigned*)((const char*)(gbase) + (voff)[_i]), (LAS unsigned*)(lds + (bufoff) + ldsw + _i * 8192), 16, 0, 0); } while (0)
; #define PG8_LDA(dst, b, h) do { _Pragma("unroll") for (int m = 0; m < 4; ++m) _Pragma("unroll") for (int k = 0; k < 2; ++k) dst[m][k] = *(const LAS bf16x8*)(lds + PG8_SA(b, h) + aoff + m * 2048 + k * 1024); } while (0)
; #define PG8_LDB(dst, b, h) do { _Pragma("unroll") for (int n = 0; n < 2; ++n) _Pragma("unroll") for (int k = 0; k < 2; ++k) dst[n][k] = *(const LAS bf16x8*)(lds + PG8_SB(b, h) + boff + n * 2048 + k * 1024); } while (0)
; #define PG8_MMA(ai, bj, At, Bt) do { __builtin_amdgcn_s_setprio(1); _Pragma("unroll") for (int m = 0; m < 4; ++m) _Pragma("unroll") for (int n = 0; n < 2; ++n) _Pragma("unroll") for (int k = 0; k < 2; ++k) \
;         acc[ai][bj][m][n] = MFMA16(Bt[n][k], At[m][k], acc[ai][bj][m][n]); __builtin_amdgcn_s_setprio(0); } while (0)
; #define PG8_WAIT_V(n) asm volatile("s_waitcnt vmcnt(" #n ")" ::: "memory")
; #define PG8_WAIT_L(n) asm volatile("s_waitcnt lgkmcnt(" #n ")" ::: "memory")
; #define PG8_BAR __builtin_amdgcn_s_barrier()
; #define PG8_SCHED __builtin_amdgcn_sched_barrier(0)
; template <class Epi>
; __device__ __forceinline__ void gemm_phase(LAS unsigned char* lds, const Gemm g, const StaticOrder& S, const Epi& E, int tid_) {
;     ...
;             PG8_WAIT_V(8); PG8_WAIT_L(0); PG8_BAR; PG8_MMA(1, 0, At, B0); PG8_MMA(1, 1, At, B1); PG8_BAR; PG8_SCHED;
;             PG8_LDB(B0, 1, 0); PG8_LDB(B1, 1, 1); PG8_SCHED; PG8_LDA(At, 1, 0); PG8_STAGE(PG8_SA(0, 1), a2 + hsA, voffA);
;             PG8_WAIT_V(8); PG8_WAIT_L(0); PG8_BAR; PG8_MMA(0, 0, At, B0); PG8_MMA(0, 1, At, B1); PG8_BAR; PG8_SCHED;
;             PG8_LDA(At, 1, 1); PG8_STAGE(PG8_SB(1, 0), b3, voffB); PG8_STAGE(PG8_SB(1, 1), b3 + hsB, voffB); PG8_STAGE(PG8_SA(1, 0), a3, voffA);
	s_setprio 1
	s_waitcnt lgkmcnt(0)
	v_mfma_f32_16x16x32_bf16 v[60:63], v[130:133], v[178:181], v[60:63]
	v_mfma_f32_16x16x32_bf16 v[56:59], v[138:141], v[178:181], v[56:59]
	v_mfma_f32_16x16x32_bf16 v[44:47], v[130:133], v[202:205], v[44:47]
	v_mfma_f32_16x16x32_bf16 v[40:43], v[138:141], v[202:205], v[40:43]
	v_mfma_f32_16x16x32_bf16 v[28:31], v[130:133], v[216:219], v[28:31]
	v_mfma_f32_16x16x32_bf16 v[24:27], v[138:141], v[216:219], v[24:27]
	v_mfma_f32_16x16x32_bf16 v[12:15], v[130:133], v[224:227], v[12:15]
	v_mfma_f32_16x16x32_bf16 v[8:11], v[138:141], v[224:227], v[8:11]
	v_mfma_f32_16x16x32_bf16 v[60:63], v[134:137], v[198:201], v[60:63]
	v_mfma_f32_16x16x32_bf16 v[56:59], v[142:145], v[198:201], v[56:59]
	v_mfma_f32_16x16x32_bf16 v[44:47], v[134:137], v[206:209], v[44:47]
	v_mfma_f32_16x16x32_bf16 v[40:43], v[142:145], v[206:209], v[40:43]
	v_mfma_f32_16x16x32_bf16 v[28:31], v[134:137], v[220:223], v[28:31]
	v_mfma_f32_16x16x32_bf16 v[24:27], v[142:145], v[220:223], v[24:27]
	v_mfma_f32_16x16x32_bf16 v[12:15], v[134:137], v[228:231], v[12:15]
	v_mfma_f32_16x16x32_bf16 v[8:11], v[142:145], v[228:231], v[8:11]
	s_setprio 0
	s_setprio 1
	v_mfma_f32_16x16x32_bf16 v[52:55], v[146:149], v[178:181], v[52:55]
	v_mfma_f32_16x16x32_bf16 v[48:51], v[170:173], v[178:181], v[48:51]
	v_mfma_f32_16x16x32_bf16 v[36:39], v[146:149], v[202:205], v[36:39]
	v_mfma_f32_16x16x32_bf16 v[32:35], v[170:173], v[202:205], v[32:35]
	v_mfma_f32_16x16x32_bf16 v[20:23], v[146:149], v[216:219], v[20:23]
	v_mfma_f32_16x16x32_bf16 v[16:19], v[170:173], v[216:219], v[16:19]
	v_mfma_f32_16x16x32_bf16 v[4:7], v[146:149], v[224:227], v[4:7]
	v_mfma_f32_16x16x32_bf16 v[0:3], v[170:173], v[224:227], v[0:3]
	v_mfma_f32_16x16x32_bf16 v[52:55], v[150:153], v[198:201], v[52:55]
	v_mfma_f32_16x16x32_bf16 v[48:51], v[174:177], v[198:201], v[48:51]
	v_mfma_f32_16x16x32_bf16 v[36:39], v[150:153], v[206:209], v[36:39]
	v_mfma_f32_16x16x32_bf16 v[32:35], v[174:177], v[206:209], v[32:35]
	v_mfma_f32_16x16x32_bf16 v[20:23], v[150:153], v[220:223], v[20:23]
	v_mfma_f32_16x16x32_bf16 v[16:19], v[174:177], v[220:223], v[16:19]
	v_mfma_f32_16x16x32_bf16 v[4:7], v[150:153], v[228:231], v[4:7]
	v_mfma_f32_16x16x32_bf16 v[0:3], v[174:177], v[228:231], v[0:3]
	s_setprio 0
	s_barrier
	s_add_i32 s70, 0, 0x18000
	s_add_i32 s71, 0, 0x1c000
	v_add_u32_e32 v142, s70, v166
	v_add_u32_e32 v169, s71, v166
	ds_read_b128 v[130:133], v142
	ds_read_b128 v[134:137], v142 offset:1024
	ds_read_b128 v[138:141], v142 offset:2048
	ds_read_b128 v[142:145], v142 offset:3072
	ds_read_b128 v[146:149], v169
	ds_read_b128 v[150:153], v169 offset:1024
	ds_read_b128 v[170:173], v169 offset:2048
	ds_read_b128 v[174:177], v169 offset:3072
	s_add_u32 s54, s54, s4
	s_addc_u32 s55, s55, 0
	s_mov_b32 m0, s58
	v_lshl_add_u64 v[244:245], s[54:55], 0, v[154:155]
	ds_read_b128 v[178:181], v168 offset:32768
	ds_read_b128 v[198:201], v168 offset:33792
	ds_read_b128 v[202:205], v168 offset:34816
	ds_read_b128 v[206:209], v168 offset:35840
	ds_read_b128 v[216:219], v168 offset:36864
	ds_read_b128 v[220:223], v168 offset:37888
	ds_read_b128 v[224:227], v168 offset:38912
	ds_read_b128 v[228:231], v168 offset:39936
	global_load_lds_dwordx4 v[244:245], off
	v_lshl_add_u64 v[244:245], s[54:55], 0, v[158:159]
	s_mov_b32 m0, s59
	s_nop 0
	global_load_lds_dwordx4 v[244:245], off
	s_waitcnt vmcnt(8)
	s_waitcnt lgkmcnt(0)
	s_barrier
	s_setprio 1
	s_waitcnt lgkmcnt(0)
	v_mfma_f32_16x16x32_bf16 v[126:129], v[130:133], v[178:181], v[126:129]
	v_mfma_f32_16x16x32_bf16 v[122:125], v[138:141], v[178:181], v[122:125]
	v_mfma_f32_16x16x32_bf16 v[110:113], v[130:133], v[202:205], v[110:113]
	v_mfma_f32_16x16x32_bf16 v[106:109], v[138:141], v[202:205], v[106:109]
	v_mfma_f32_16x16x32_bf16 v[94:97], v[130:133], v[216:219], v[94:97]
	v_mfma_f32_16x16x32_bf16 v[90:93], v[138:141], v[216:219], v[90:93]
	v_mfma_f32_16x16x32_bf16 v[76:79], v[130:133], v[224:227], v[76:79]
	v_mfma_f32_16x16x32_bf16 v[72:75], v[138:141], v[224:227], v[72:75]
	v_mfma_f32_16x16x32_bf16 v[126:129], v[134:137], v[198:201], v[126:129]
	v_mfma_f32_16x16x32_bf16 v[122:125], v[142:145], v[198:201], v[122:125]
	v_mfma_f32_16x16x32_bf16 v[110:113], v[134:137], v[206:209], v[110:113]
	v_mfma_f32_16x16x32_bf16 v[106:109], v[142:145], v[206:209], v[106:109]
	v_mfma_f32_16x16x32_bf16 v[94:97], v[134:137], v[220:223], v[94:97]
	v_mfma_f32_16x16x32_bf16 v[90:93], v[142:145], v[220:223], v[90:93]
	v_mfma_f32_16x16x32_bf16 v[76:79], v[134:137], v[228:231], v[76:79]
	v_mfma_f32_16x16x32_bf16 v[72:75], v[142:145], v[228:231], v[72:75]
	s_setprio 0
	s_setprio 1
	v_mfma_f32_16x16x32_bf16 v[118:121], v[146:149], v[178:181], v[118:121]
	v_mfma_f32_16x16x32_bf16 v[114:117], v[170:173], v[178:181], v[114:117]
	v_mfma_f32_16x16x32_bf16 v[102:105], v[146:149], v[202:205], v[102:105]
	v_mfma_f32_16x16x32_bf16 v[98:101], v[170:173], v[202:205], v[98:101]
	v_mfma_f32_16x16x32_bf16 v[86:89], v[146:149], v[216:219], v[86:89]
	v_mfma_f32_16x16x32_bf16 v[82:85], v[170:173], v[216:219], v[82:85]
	v_mfma_f32_16x16x32_bf16 v[68:71], v[146:149], v[224:227], v[68:71]
	v_mfma_f32_16x16x32_bf16 v[64:67], v[170:173], v[224:227], v[64:67]
	v_mfma_f32_16x16x32_bf16 v[118:121], v[150:153], v[198:201], v[118:121]
	v_mfma_f32_16x16x32_bf16 v[114:117], v[174:177], v[198:201], v[114:117]
	v_mfma_f32_16x16x32_bf16 v[102:105], v[150:153], v[206:209], v[102:105]
	v_mfma_f32_16x16x32_bf16 v[98:101], v[174:177], v[206:209], v[98:101]
	v_mfma_f32_16x16x32_bf16 v[86:89], v[150:153], v[220:223], v[86:89]
	v_mfma_f32_16x16x32_bf16 v[82:85], v[174:177], v[220:223], v[82:85]
	v_mfma_f32_16x16x32_bf16 v[68:71], v[150:153], v[228:231], v[68:71]
	v_mfma_f32_16x16x32_bf16 v[64:67], v[174:177], v[228:231], v[64:67]
	s_setprio 0
	s_barrier
; #define PG8_STAGE(bufoff, gbase, voff) do { _Pragma("unroll") for (int _i = 0; _i < 2; ++_i) \
;         __builtin_amdgcn_global_load_lds((const unsigned*)((const char*)(gbase) + (voff)[_i]), (LAS unsigned*)(lds + (bufoff) + ldsw + _i * 8192), 16, 0, 0); } while (0)
; #define PG8_LDA(dst, b, h) do { _Pragma("unroll") for (int m = 0; m < 4; ++m) _Pragma("unroll") for (int k = 0; k < 2; ++k) dst[m][k] = *(const LAS bf16x8*)(lds + PG8_SA(b, h) + aoff + m * 2048 + k * 1024); } while (0)
; #define PG8_MMA(ai, bj, At, Bt) do { __builtin_amdgcn_s_setprio(1); _Pragma("unroll") for (int m = 0; m < 4; ++m) _Pragma("unroll") for (int n = 0; n < 2; ++n) _Pragma("unroll") for (int k = 0; k < 2; ++k) \
;         acc[ai][bj][m][n] = MFMA16(Bt[n][k], At[m][k], acc[ai][bj][m][n]); __builtin_amdgcn_s_setprio(0); } while (0)
; #define PG8_WAIT_V(n) asm volatile("s_waitcnt vmcnt(" #n ")" ::: "memory")
; #define PG8_WAIT_L(n) asm volatile("s_waitcnt lgkmcnt(" #n ")" ::: "memory")
; #define PG8_BAR __builtin_amdgcn_s_barrier()
; #define PG8_SCHED __builtin_amdgcn_sched_barrier(0)
; template <class Epi>
; __device__ __forceinline__ void gemm_phase(LAS unsigned char* lds, const Gemm g, const StaticOrder& S, const Epi& E, int tid_) {
;     ...
;             PG8_LDA(At, 1, 1); PG8_STAGE(PG8_SB(1, 0), b3, voffB); PG8_STAGE(PG8_SB(1, 1), b3 + hsB, voffB); PG8_STAGE(PG8_SA(1, 0), a3, voffA);
;             PG8_WAIT_V(8); PG8_WAIT_L(0); PG8_BAR; PG8_MMA(1, 0, At, B0); PG8_MMA(1, 1, At, B1); PG8_BAR; PG8_SCHED;
;         }
	s_add_i32 s54, s70, s31
	v_lshl_add_u64 v[232:233], v[232:233], 0, s[6:7]
	s_mov_b32 m0, s54
	ds_read_b128 v[178:181], v168 offset:49152
	ds_read_b128 v[198:201], v168 offset:50176
	ds_read_b128 v[202:205], v168 offset:51200
	ds_read_b128 v[206:209], v168 offset:52224
	ds_read_b128 v[216:219], v168 offset:53248
	ds_read_b128 v[220:223], v168 offset:54272
	ds_read_b128 v[224:227], v168 offset:55296
	ds_read_b128 v[228:231], v168 offset:56320
	global_load_lds_dwordx4 v[232:233], off
	v_lshl_add_u64 v[232:233], v[234:235], 0, s[6:7]
	s_add_i32 m0, s54, 0x2000
	s_add_i32 s54, s71, s31
	global_load_lds_dwordx4 v[232:233], off
	v_lshl_add_u64 v[232:233], v[236:237], 0, s[6:7]
	s_mov_b32 m0, s54
	s_nop 0
	global_load_lds_dwordx4 v[232:233], off
	v_lshl_add_u64 v[232:233], v[238:239], 0, s[6:7]
	s_add_i32 m0, s54, 0x2000
	s_nop 0
	global_load_lds_dwordx4 v[232:233], off
	v_lshl_add_u64 v[232:233], v[240:241], 0, s[6:7]
	s_mov_b32 m0, s60
	s_nop 0
	global_load_lds_dwordx4 v[232:233], off
	v_lshl_add_u64 v[232:233], v[242:243], 0, s[6:7]
	s_mov_b32 m0, s61
	s_nop 0
	global_load_lds_dwordx4 v[232:233], off
	s_waitcnt vmcnt(8)
	s_waitcnt lgkmcnt(0)
	s_barrier
	s_setprio 1
	s_waitcnt lgkmcnt(0)
	v_mfma_f32_16x16x32_bf16 v[60:63], v[130:133], v[178:181], v[60:63]
	v_mfma_f32_16x16x32_bf16 v[56:59], v[138:141], v[178:181], v[56:59]
	v_mfma_f32_16x16x32_bf16 v[44:47], v[130:133], v[202:205], v[44:47]
	v_mfma_f32_16x16x32_bf16 v[40:43], v[138:141], v[202:205], v[40:43]
	v_mfma_f32_16x16x32_bf16 v[28:31], v[130:133], v[216:219], v[28:31]
	v_mfma_f32_16x16x32_bf16 v[24:27], v[138:141], v[216:219], v[24:27]
	v_mfma_f32_16x16x32_bf16 v[12:15], v[130:133], v[224:227], v[12:15]
	v_mfma_f32_16x16x32_bf16 v[8:11], v[138:141], v[224:227], v[8:11]
	v_mfma_f32_16x16x32_bf16 v[60:63], v[134:137], v[198:201], v[60:63]
	v_mfma_f32_16x16x32_bf16 v[56:59], v[142:145], v[198:201], v[56:59]
	v_mfma_f32_16x16x32_bf16 v[44:47], v[134:137], v[206:209], v[44:47]
	v_mfma_f32_16x16x32_bf16 v[40:43], v[142:145], v[206:209], v[40:43]
	v_mfma_f32_16x16x32_bf16 v[28:31], v[134:137], v[220:223], v[28:31]
	v_mfma_f32_16x16x32_bf16 v[24:27], v[142:145], v[220:223], v[24:27]
	v_mfma_f32_16x16x32_bf16 v[12:15], v[134:137], v[228:231], v[12:15]
	v_mfma_f32_16x16x32_bf16 v[8:11], v[142:145], v[228:231], v[8:11]
	s_setprio 0
	s_setprio 1
	v_mfma_f32_16x16x32_bf16 v[52:55], v[146:149], v[178:181], v[52:55]
	v_mfma_f32_16x16x32_bf16 v[48:51], v[170:173], v[178:181], v[48:51]
	v_mfma_f32_16x16x32_bf16 v[36:39], v[146:149], v[202:205], v[36:39]
	v_mfma_f32_16x16x32_bf16 v[32:35], v[170:173], v[202:205], v[32:35]
	v_mfma_f32_16x16x32_bf16 v[20:23], v[146:149], v[216:219], v[20:23]
	v_mfma_f32_16x16x32_bf16 v[16:19], v[170:173], v[216:219], v[16:19]
	v_mfma_f32_16x16x32_bf16 v[4:7], v[146:149], v[224:227], v[4:7]
	v_mfma_f32_16x16x32_bf16 v[0:3], v[170:173], v[224:227], v[0:3]
	v_mfma_f32_16x16x32_bf16 v[52:55], v[150:153], v[198:201], v[52:55]
	v_mfma_f32_16x16x32_bf16 v[48:51], v[174:177], v[198:201], v[48:51]
	v_mfma_f32_16x16x32_bf16 v[36:39], v[150:153], v[206:209], v[36:39]
	v_mfma_f32_16x16x32_bf16 v[32:35], v[174:177], v[206:209], v[32:35]
	v_mfma_f32_16x16x32_bf16 v[20:23], v[150:153], v[220:223], v[20:23]
	v_mfma_f32_16x16x32_bf16 v[16:19], v[174:177], v[220:223], v[16:19]
	v_mfma_f32_16x16x32_bf16 v[4:7], v[150:153], v[228:231], v[4:7]
	v_mfma_f32_16x16x32_bf16 v[0:3], v[174:177], v[228:231], v[0:3]
	s_setprio 0
	s_barrier
	s_add_u32 s28, s28, 0x100
	s_addc_u32 s29, s29, 0
	s_add_u32 s22, s22, 0x100
	s_addc_u32 s23, s23, 0
	s_cmp_ge_i32 s69, s1
	s_mov_b32 s54, s69
	s_cbranch_scc0 .LBB0_683
; __device__ __forceinline__ float bf_lo(unsigned w) { return (float)__builtin_bit_cast(h16x2, w).x; }
; __device__ __forceinline__ float bf_hi(unsigned w) { return (float)__builtin_bit_cast(h16x2, w).y; }
; __device__ __forceinline__ float bf_lo(unsigned w) { return __uint_as_float(w << 16); }
; __device__ __forceinline__ float bf_hi(unsigned w) { return __uint_as_float(w & 0xffff0000u); }
; template <int MASK> __device__ __forceinline__ float swz_xor(float v) { return __int_as_float(__builtin_amdgcn_ds_swizzle(__float_as_int(v), (MASK << 10) | 0x1F)); }
; #define PG8_BAR __builtin_amdgcn_s_barrier()
; template <class Epi>
; __device__ __forceinline__ void gemm_phase(LAS unsigned char* lds, const Gemm g, const StaticOrder& S, const Epi& E, int tid_) {
;     ...
;         if (wr == 0) PG8_BAR;
;     __device__ __forceinline__ void operator()(const Acc& acc, const pg8::Unit& u, int wr, int wc, int fr, int fq, LAS float* rcache, int& cached_pm) const {
;         const int row0 = u.pm * 256 + wr * 64 + fr, col0 = u.pn * 256 + wc * 32 + 8 * fq;
; #pragma unroll
;         for (int ai = 0; ai < 2; ++ai) {
;             u32x4 rw[4][2];
; #pragma unroll
;             for (int m = 0; m < 4; ++m)
; #pragma unroll
;                 for (int bj = 0; bj < 2; ++bj) rw[m][bj] = *at<const u32x4>(hb, (unsigned)((row0 + ai * 128 + m * 16) * DM + col0 + bj * 128) * 2u);
; #pragma unroll
;             for (int m = 0; m < 4; ++m) {
;                 const int row = row0 + ai * 128 + m * 16; const unsigned off = (unsigned)(row * DM + col0); float ss = 0.f;
; #pragma unroll
;                 for (int bj = 0; bj < 2; ++bj) {
;                     const u32x4 w = rw[m][bj];
;                     const f32x4 r0 = (f32x4){bf_lo(w.x), bf_hi(w.x), bf_lo(w.y), bf_hi(w.y)}, r1 = (f32x4){bf_lo(w.z), bf_hi(w.z), bf_lo(w.w), bf_hi(w.w)};
;                     const f32x4 v0 = r0 + acc[ai][bj][m][0] * scale, v1 = r1 + acc[ai][bj][m][1] * scale;
;                     *at<u32x4>(hb, (off + bj * 128) * 2u) = pack8_rne(v0, v1);
;                     ss += (v0[0] * v0[0] + v0[1] * v0[1]) + (v0[2] * v0[2] + v0[3] * v0[3]) + (v1[0] * v1[0] + v1[1] * v1[1]) + (v1[2] * v1[2] + v1[3] * v1[3]);
;                 }
;                 ss += swz_xor<16>(ss); ss = sum_x32(ss);
;                 if (fq == 0) *at<float>(ssq, (unsigned)(row * 16 + u.pn * 4 + wc) * 4u) = ss;
.LBB0_685:
.LBB0_686:
	v_lshl_add_u32 v169, s2, 8, v81
	v_lshl_or_b32 v170, s18, 9, v167
	v_lshl_add_u32 v171, v169, 11, v170
	global_load_dwordx4 v[172:175], v171, s[86:87]
	v_or_b32_e32 v200, 0x100, v171
	global_load_dwordx4 v[176:179], v200, s[86:87]
	v_add_u32_e32 v130, 0x8000, v171
	v_add_u32_e32 v131, 0x8100, v171
	v_add_u32_e32 v132, 0x10000, v171
	v_add_u32_e32 v133, 0x10100, v171
	v_add_u32_e32 v134, 0x18000, v171
	v_add_u32_e32 v180, 0x18100, v171
	global_load_dwordx4 v[150:153], v130, s[86:87]
	global_load_dwordx4 v[146:149], v131, s[86:87]
	global_load_dwordx4 v[142:145], v132, s[86:87]
	global_load_dwordx4 v[138:141], v133, s[86:87]
	s_nop 0
	global_load_dwordx4 v[134:137], v134, s[86:87]
	s_nop 0
	global_load_dwordx4 v[130:133], v180, s[86:87]
	v_add_u32_e32 v240, 0x40000, v171
	global_load_dwordx4 v[202:205], v240, s[86:87]
	v_add_u32_e32 v240, 0x40100, v171
	global_load_dwordx4 v[206:209], v240, s[86:87]
	v_add_u32_e32 v240, 0x48000, v171
	global_load_dwordx4 v[216:219], v240, s[86:87]
	v_add_u32_e32 v240, 0x48100, v171
	global_load_dwordx4 v[220:223], v240, s[86:87]
	v_add_u32_e32 v240, 0x50000, v171
	global_load_dwordx4 v[224:227], v240, s[86:87]
	v_add_u32_e32 v240, 0x50100, v171
	global_load_dwordx4 v[228:231], v240, s[86:87]
	v_add_u32_e32 v240, 0x58000, v171
	global_load_dwordx4 v[232:235], v240, s[86:87]
	v_add_u32_e32 v240, 0x58100, v171
	global_load_dwordx4 v[236:239], v240, s[86:87]
	s_and_b64 vcc, exec, s[50:51]
	s_cbranch_vccz .Lres_noalign
	s_barrier
.Lres_noalign:
	s_waitcnt vmcnt(8)
	v_lshlrev_b32_e32 v180, 16, v172
	v_and_b32_e32 v181, 0xffff0000, v172
	v_lshlrev_b32_e32 v172, 16, v173
	v_and_b32_e32 v173, 0xffff0000, v173
	v_lshlrev_b32_e32 v198, 16, v174
	v_and_b32_e32 v199, 0xffff0000, v174
	v_lshlrev_b32_e32 v174, 16, v175
	v_and_b32_e32 v175, 0xffff0000, v175
	v_pk_fma_f32 v[126:127], s[16:17], v[126:127], v[180:181]
	v_lshlrev_b32_e32 v180, 16, v176
	v_and_b32_e32 v181, 0xffff0000, v176
	v_lshlrev_b32_e32 v176, 16, v177
	v_and_b32_e32 v177, 0xffff0000, v177
	v_pk_fma_f32 v[128:129], s[44:45], v[128:129], v[172:173]
	v_pk_fma_f32 v[172:173], s[44:45], v[124:125], v[174:175]
	v_pk_fma_f32 v[174:175], s[16:17], v[122:123], v[198:199]
	v_lshlrev_b32_e32 v198, 16, v178
	v_and_b32_e32 v199, 0xffff0000, v178
	v_lshlrev_b32_e32 v178, 16, v179
	v_and_b32_e32 v179, 0xffff0000, v179
	v_pk_fma_f32 v[120:121], s[44:45], v[120:121], v[176:177]
	v_pk_fma_f32 v[118:119], s[16:17], v[118:119], v[180:181]
	v_cvt_pk_bf16_f32 v122, v126, v127
	v_cvt_pk_bf16_f32 v123, v128, v129
	v_cvt_pk_bf16_f32 v124, v174, v175
	v_cvt_pk_bf16_f32 v125, v172, v173
	v_mul_f32_e32 v127, v127, v127
	v_mul_f32_e32 v129, v129, v129
	v_pk_fma_f32 v[176:177], s[44:45], v[116:117], v[178:179]
	v_pk_fma_f32 v[116:117], s[16:17], v[114:115], v[198:199]
	v_cvt_pk_bf16_f32 v114, v118, v119
	v_mul_f32_e32 v115, v119, v119
	v_mul_f32_e32 v119, v121, v121
	v_mul_f32_e32 v175, v175, v175
	global_store_dwordx4 v171, v[122:125], s[86:87]
	v_fmac_f32_e32 v127, v126, v126
	v_fmac_f32_e32 v129, v128, v128
	v_mul_f32_e32 v122, v117, v117
	v_fmac_f32_e32 v115, v118, v118
	v_fmac_f32_e32 v119, v120, v120
	v_mul_f32_e32 v173, v173, v173
	v_fmac_f32_e32 v175, v174, v174
	v_mul_f32_e32 v123, v177, v177
	v_add_f32_e32 v124, v127, v129
	v_fmac_f32_e32 v122, v116, v116
	v_add_f32_e32 v115, v115, v119
	v_fmac_f32_e32 v173, v172, v172
	v_fmac_f32_e32 v123, v176, v176
	v_add_f32_e32 v118, v175, v124
	v_add_f32_e32 v115, v122, v115
	v_add_f32_e32 v118, v173, v118
	v_add_f32_e32 v115, v123, v115
	v_add_f32_e32 v118, v118, v115
	ds_swizzle_b32 v119, v118 offset:swizzle(SWAP,16)
	v_cvt_pk_bf16_f32 v115, v120, v121
	v_cvt_pk_bf16_f32 v116, v116, v117
	v_cvt_pk_bf16_f32 v117, v176, v177
	global_store_dwordx4 v200, v[114:117], s[86:87]
	s_waitcnt lgkmcnt(0)
	s_nop 0
	v_add_f32_e32 v114, v118, v119
	v_mov_b32_e32 v115, v114
	s_nop 1
	v_permlane32_swap_b32_e32 v114, v115
	s_and_saveexec_b64 s[28:29], s[36:37]
	s_cbranch_execz .LBB0_688
	v_lshl_or_b32 v116, v169, 6, s64
	v_lshl_add_u32 v116, s18, 4, v116
	v_add_f32_e32 v114, v114, v115
	global_store_dword v116, v114, s[92:93]

; __device__ __forceinline__ float bf_lo(unsigned w) { return (float)__builtin_bit_cast(h16x2, w).x; }
; __device__ __forceinline__ float bf_hi(unsigned w) { return (float)__builtin_bit_cast(h16x2, w).y; }
; __device__ __forceinline__ float bf_lo(unsigned w) { return __uint_as_float(w << 16); }
; __device__ __forceinline__ float bf_hi(unsigned w) { return __uint_as_float(w & 0xffff0000u); }
; template <int MASK> __device__ __forceinline__ float swz_xor(float v) { return __int_as_float(__builtin_amdgcn_ds_swizzle(__float_as_int(v), (MASK << 10) | 0x1F)); }
; __device__ __forceinline__ float sum_x32(float v) { const auto rr = __builtin_amdgcn_permlane32_swap(__float_as_uint(v), __float_as_uint(v), false, false); return __uint_as_float(rr[0]) + __uint_as_float(rr[1]); }
; __device__ __forceinline__ u32x4 pack8_rne(const f32x4 a, const f32x4 b) { u32x4 w; w.x = cvt_pk_bf16(a[0], a[1]); w.y = cvt_pk_bf16(a[2], a[3]); w.z = cvt_pk_bf16(b[0], b[1]); w.w = cvt_pk_bf16(b[2], b[3]); return w; }
; template <class T> __device__ __forceinline__ T* at(const void* base, unsigned byteoff) { return (T*)((char*)base + byteoff); }
;     __device__ __forceinline__ void operator()(const Acc& acc, const pg8::Unit& u, int wr, int wc, int fr, int fq, LAS float* rcache, int& cached_pm) const {
;     ...
;             for (int m = 0; m < 4; ++m) {
;                 const int row = row0 + ai * 128 + m * 16; const unsigned off = (unsigned)(row * DM + col0); float ss = 0.f;
; #pragma unroll
;                 for (int bj = 0; bj < 2; ++bj) {
;                     const u32x4 w = rw[m][bj];
;                     const f32x4 r0 = (f32x4){bf_lo(w.x), bf_hi(w.x), bf_lo(w.y), bf_hi(w.y)}, r1 = (f32x4){bf_lo(w.z), bf_hi(w.z), bf_lo(w.w), bf_hi(w.w)};
;                     const f32x4 v0 = r0 + acc[ai][bj][m][0] * scale, v1 = r1 + acc[ai][bj][m][1] * scale;
;                     *at<u32x4>(hb, (off + bj * 128) * 2u) = pack8_rne(v0, v1);
;                     ss += (v0[0] * v0[0] + v0[1] * v0[1]) + (v0[2] * v0[2] + v0[3] * v0[3]) + (v1[0] * v1[0] + v1[1] * v1[1]) + (v1[2] * v1[2] + v1[3] * v1[3]);
;                 }
;                 ss += swz_xor<16>(ss); ss = sum_x32(ss);
;                 if (fq == 0) *at<float>(ssq, (unsigned)(row * 16 + u.pn * 4 + wc) * 4u) = ss;
.LBB0_694:
	s_or_b64 exec, exec, s[28:29]
	v_add_u32_e32 v90, 0x80, v169
	v_lshl_add_u32 v91, v90, 11, v170
	s_waitcnt vmcnt(8)
	v_lshlrev_b32_e32 v100, 16, v202
	v_and_b32_e32 v101, 0xffff0000, v202
	v_lshlrev_b32_e32 v92, 16, v203
	v_and_b32_e32 v93, 0xffff0000, v203
	v_lshlrev_b32_e32 v102, 16, v204
	v_and_b32_e32 v103, 0xffff0000, v204
	v_lshlrev_b32_e32 v94, 16, v205
	v_and_b32_e32 v95, 0xffff0000, v205
	v_pk_fma_f32 v[62:63], s[44:45], v[62:63], v[92:93]
	v_pk_fma_f32 v[60:61], s[16:17], v[60:61], v[100:101]
	v_pk_fma_f32 v[92:93], s[44:45], v[58:59], v[94:95]
	v_pk_fma_f32 v[94:95], s[16:17], v[56:57], v[102:103]
	v_cvt_pk_bf16_f32 v56, v60, v61
	v_cvt_pk_bf16_f32 v57, v62, v63
	v_cvt_pk_bf16_f32 v58, v94, v95
	v_cvt_pk_bf16_f32 v59, v92, v93
	global_store_dwordx4 v91, v[56:59], s[86:87]
	s_nop 1
	v_mul_f32_e32 v56, v61, v61
	v_mul_f32_e32 v57, v63, v63
	v_fmac_f32_e32 v56, v60, v60
	v_fmac_f32_e32 v57, v62, v62
	v_add_f32_e32 v56, v56, v57
	v_mul_f32_e32 v57, v95, v95
	v_fmac_f32_e32 v57, v94, v94
	v_add_f32_e32 v56, v57, v56
	v_mul_f32_e32 v57, v93, v93
	v_fmac_f32_e32 v57, v92, v92
	v_add_f32_e32 v92, v57, v56
	v_lshlrev_b32_e32 v56, 16, v206
	v_and_b32_e32 v57, 0xffff0000, v206
	v_lshlrev_b32_e32 v58, 16, v207
	v_and_b32_e32 v59, 0xffff0000, v207
	v_pk_fma_f32 v[52:53], s[16:17], v[52:53], v[56:57]
	v_lshlrev_b32_e32 v60, 16, v208
	v_and_b32_e32 v61, 0xffff0000, v208
	v_pk_fma_f32 v[54:55], s[44:45], v[54:55], v[58:59]
	v_cvt_pk_bf16_f32 v56, v52, v53
	v_mul_f32_e32 v53, v53, v53
	v_pk_fma_f32 v[48:49], s[16:17], v[48:49], v[60:61]
	v_fmac_f32_e32 v53, v52, v52
	v_mul_f32_e32 v52, v55, v55
	v_lshlrev_b32_e32 v62, 16, v209
	v_and_b32_e32 v63, 0xffff0000, v209
	v_cvt_pk_bf16_f32 v58, v48, v49
	v_fmac_f32_e32 v52, v54, v54
	v_mul_f32_e32 v49, v49, v49
	v_pk_fma_f32 v[50:51], s[44:45], v[50:51], v[62:63]
	v_add_f32_e32 v52, v53, v52
	v_fmac_f32_e32 v49, v48, v48
	v_add_f32_e32 v48, v49, v52
	v_mul_f32_e32 v49, v51, v51
	v_fmac_f32_e32 v49, v50, v50
	v_add_f32_e32 v48, v49, v48
	v_add_f32_e32 v48, v92, v48
	ds_swizzle_b32 v49, v48 offset:swizzle(SWAP,16)
	v_cvt_pk_bf16_f32 v57, v54, v55
	v_cvt_pk_bf16_f32 v59, v50, v51
	v_or_b32_e32 v60, 0x100, v91
	global_store_dwordx4 v60, v[56:59], s[86:87]
	s_waitcnt lgkmcnt(0)
	v_add_f32_e32 v48, v48, v49
	v_mov_b32_e32 v49, v48
	s_nop 1
	v_permlane32_swap_b32_e32 v48, v49
	s_and_saveexec_b64 s[28:29], s[36:37]
	s_cbranch_execz .LBB0_696
	s_lshl_b32 s2, s18, 4
	s_or_b32 s2, s2, s64
	v_lshl_add_u32 v50, v90, 6, s2
	v_add_f32_e32 v48, v48, v49
	global_store_dword v50, v48, s[92:93]
.LBB0_696:
	s_or_b64 exec, exec, s[28:29]
	v_lshlrev_b32_e32 v50, 16, v216
	v_and_b32_e32 v51, 0xffff0000, v216
	v_lshlrev_b32_e32 v52, 16, v217
	v_and_b32_e32 v53, 0xffff0000, v217
	v_lshlrev_b32_e32 v54, 16, v218
	v_and_b32_e32 v55, 0xffff0000, v218
	v_lshlrev_b32_e32 v56, 16, v219
	v_and_b32_e32 v57, 0xffff0000, v219
	v_add_u32_e32 v48, 0x90, v169
	v_pk_fma_f32 v[46:47], s[44:45], v[46:47], v[52:53]
	v_pk_fma_f32 v[44:45], s[16:17], v[44:45], v[50:51]
	v_pk_fma_f32 v[50:51], s[44:45], v[42:43], v[56:57]
	v_pk_fma_f32 v[52:53], s[16:17], v[40:41], v[54:55]
	v_lshl_add_u32 v49, v48, 11, v170
	v_cvt_pk_bf16_f32 v40, v44, v45
	v_cvt_pk_bf16_f32 v41, v46, v47
	v_cvt_pk_bf16_f32 v42, v52, v53
	v_cvt_pk_bf16_f32 v43, v50, v51
	global_store_dwordx4 v49, v[40:43], s[86:87]
	s_nop 1
	v_mul_f32_e32 v40, v45, v45
	v_mul_f32_e32 v41, v47, v47
	v_fmac_f32_e32 v40, v44, v44
	v_fmac_f32_e32 v41, v46, v46
	v_add_f32_e32 v40, v40, v41
	v_mul_f32_e32 v41, v53, v53
	v_fmac_f32_e32 v41, v52, v52
	v_add_f32_e32 v40, v41, v40
	v_mul_f32_e32 v41, v51, v51
	v_fmac_f32_e32 v41, v50, v50
	v_add_f32_e32 v50, v41, v40
	v_lshlrev_b32_e32 v40, 16, v220
	v_and_b32_e32 v41, 0xffff0000, v220
	v_lshlrev_b32_e32 v42, 16, v221
	v_and_b32_e32 v43, 0xffff0000, v221
	v_lshlrev_b32_e32 v44, 16, v222
	v_and_b32_e32 v45, 0xffff0000, v222
	v_lshlrev_b32_e32 v46, 16, v223
	v_and_b32_e32 v47, 0xffff0000, v223
	v_pk_fma_f32 v[36:37], s[16:17], v[36:37], v[40:41]
	v_pk_fma_f32 v[38:39], s[44:45], v[38:39], v[42:43]
	v_pk_fma_f32 v[40:41], s[44:45], v[34:35], v[46:47]
	v_pk_fma_f32 v[34:35], s[16:17], v[32:33], v[44:45]
	v_cvt_pk_bf16_f32 v32, v36, v37
	v_mul_f32_e32 v37, v37, v37
	v_fmac_f32_e32 v37, v36, v36
	v_mul_f32_e32 v36, v39, v39
	v_fmac_f32_e32 v36, v38, v38
	v_add_f32_e32 v36, v37, v36
	v_mul_f32_e32 v37, v35, v35
	v_fmac_f32_e32 v37, v34, v34
	v_add_f32_e32 v36, v37, v36
	v_mul_f32_e32 v37, v41, v41
	v_fmac_f32_e32 v37, v40, v40
	v_add_f32_e32 v36, v37, v36
	v_add_f32_e32 v36, v50, v36
	ds_swizzle_b32 v37, v36 offset:swizzle(SWAP,16)
	v_cvt_pk_bf16_f32 v33, v38, v39
	v_cvt_pk_bf16_f32 v34, v34, v35
	v_cvt_pk_bf16_f32 v35, v40, v41
	v_or_b32_e32 v38, 0x100, v49
	global_store_dwordx4 v38, v[32:35], s[86:87]
	s_waitcnt lgkmcnt(0)
	s_nop 0
	v_add_f32_e32 v32, v36, v37
	v_mov_b32_e32 v33, v32
	s_nop 1
	v_permlane32_swap_b32_e32 v32, v33
	s_and_saveexec_b64 s[28:29], s[36:37]
	s_cbranch_execz .LBB0_698
	s_lshl_b32 s2, s18, 4
	s_or_b32 s2, s2, s64
	v_lshl_add_u32 v34, v48, 6, s2
	v_add_f32_e32 v32, v32, v33
	global_store_dword v34, v32, s[92:93]
; __device__ __forceinline__ float bf_lo(unsigned w) { return (float)__builtin_bit_cast(h16x2, w).x; }
; __device__ __forceinline__ float bf_hi(unsigned w) { return (float)__builtin_bit_cast(h16x2, w).y; }
; __device__ __forceinline__ float bf_lo(unsigned w) { return __uint_as_float(w << 16); }
; __device__ __forceinline__ float bf_hi(unsigned w) { return __uint_as_float(w & 0xffff0000u); }
; template <int MASK> __device__ __forceinline__ float swz_xor(float v) { return __int_as_float(__builtin_amdgcn_ds_swizzle(__float_as_int(v), (MASK << 10) | 0x1F)); }
; __device__ __forceinline__ float sum_x32(float v) { const auto rr = __builtin_amdgcn_permlane32_swap(__float_as_uint(v), __float_as_uint(v), false, false); return __uint_as_float(rr[0]) + __uint_as_float(rr[1]); }
; __device__ __forceinline__ u32x4 pack8_rne(const f32x4 a, const f32x4 b) { u32x4 w; w.x = cvt_pk_bf16(a[0], a[1]); w.y = cvt_pk_bf16(a[2], a[3]); w.z = cvt_pk_bf16(b[0], b[1]); w.w = cvt_pk_bf16(b[2], b[3]); return w; }
;     __device__ __forceinline__ void operator()(const Acc& acc, const pg8::Unit& u, int wr, int wc, int fr, int fq, LAS float* rcache, int& cached_pm) const {
;     ...
;                 for (int bj = 0; bj < 2; ++bj) rw[m][bj] = *at<const u32x4>(hb, (unsigned)((row0 + ai * 128 + m * 16) * DM + col0 + bj * 128) * 2u);
; #pragma unroll
;             for (int m = 0; m < 4; ++m) {
;                 const int row = row0 + ai * 128 + m * 16; const unsigned off = (unsigned)(row * DM + col0); float ss = 0.f;
; #pragma unroll
;                 for (int bj = 0; bj < 2; ++bj) {
;                     const u32x4 w = rw[m][bj];
;                     const f32x4 r0 = (f32x4){bf_lo(w.x), bf_hi(w.x), bf_lo(w.y), bf_hi(w.y)}, r1 = (f32x4){bf_lo(w.z), bf_hi(w.z), bf_lo(w.w), bf_hi(w.w)};
;                     const f32x4 v0 = r0 + acc[ai][bj][m][0] * scale, v1 = r1 + acc[ai][bj][m][1] * scale;
;                     *at<u32x4>(hb, (off + bj * 128) * 2u) = pack8_rne(v0, v1);
;                     ss += (v0[0] * v0[0] + v0[1] * v0[1]) + (v0[2] * v0[2] + v0[3] * v0[3]) + (v1[0] * v1[0] + v1[1] * v1[1]) + (v1[2] * v1[2] + v1[3] * v1[3]);
;                 }
;                 ss += swz_xor<16>(ss); ss = sum_x32(ss);
;                 if (fq == 0) *at<float>(ssq, (unsigned)(row * 16 + u.pn * 4 + wc) * 4u) = ss;
;             }
.LBB0_698:
	s_or_b64 exec, exec, s[28:29]
	v_lshlrev_b32_e32 v34, 16, v224
	v_and_b32_e32 v35, 0xffff0000, v224
	v_lshlrev_b32_e32 v36, 16, v225
	v_and_b32_e32 v37, 0xffff0000, v225
	v_lshlrev_b32_e32 v38, 16, v226
	v_and_b32_e32 v39, 0xffff0000, v226
	v_lshlrev_b32_e32 v40, 16, v227
	v_and_b32_e32 v41, 0xffff0000, v227
	v_add_u32_e32 v32, 0xa0, v169
	v_pk_fma_f32 v[30:31], s[44:45], v[30:31], v[36:37]
	v_pk_fma_f32 v[28:29], s[16:17], v[28:29], v[34:35]
	v_pk_fma_f32 v[34:35], s[44:45], v[26:27], v[40:41]
	v_pk_fma_f32 v[36:37], s[16:17], v[24:25], v[38:39]
	v_lshl_add_u32 v33, v32, 11, v170
	v_cvt_pk_bf16_f32 v24, v28, v29
	v_cvt_pk_bf16_f32 v25, v30, v31
	v_cvt_pk_bf16_f32 v26, v36, v37
	v_cvt_pk_bf16_f32 v27, v34, v35
	global_store_dwordx4 v33, v[24:27], s[86:87]
	s_nop 1
	v_mul_f32_e32 v24, v29, v29
	v_mul_f32_e32 v25, v31, v31
	v_fmac_f32_e32 v24, v28, v28
	v_fmac_f32_e32 v25, v30, v30
	v_add_f32_e32 v24, v24, v25
	v_mul_f32_e32 v25, v37, v37
	v_fmac_f32_e32 v25, v36, v36
	v_add_f32_e32 v24, v25, v24
	v_mul_f32_e32 v25, v35, v35
	v_fmac_f32_e32 v25, v34, v34
	v_add_f32_e32 v34, v25, v24
	v_lshlrev_b32_e32 v24, 16, v228
	v_and_b32_e32 v25, 0xffff0000, v228
	v_lshlrev_b32_e32 v26, 16, v229
	v_and_b32_e32 v27, 0xffff0000, v229
	v_lshlrev_b32_e32 v28, 16, v230
	v_and_b32_e32 v29, 0xffff0000, v230
	v_lshlrev_b32_e32 v30, 16, v231
	v_and_b32_e32 v31, 0xffff0000, v231
	v_pk_fma_f32 v[20:21], s[16:17], v[20:21], v[24:25]
	v_pk_fma_f32 v[22:23], s[44:45], v[22:23], v[26:27]
	v_pk_fma_f32 v[24:25], s[44:45], v[18:19], v[30:31]
	v_pk_fma_f32 v[18:19], s[16:17], v[16:17], v[28:29]
	v_cvt_pk_bf16_f32 v16, v20, v21
	v_mul_f32_e32 v21, v21, v21
	v_fmac_f32_e32 v21, v20, v20
	v_mul_f32_e32 v20, v23, v23
	v_fmac_f32_e32 v20, v22, v22
	v_add_f32_e32 v20, v21, v20
	v_mul_f32_e32 v21, v19, v19
	v_fmac_f32_e32 v21, v18, v18
	v_add_f32_e32 v20, v21, v20
	v_mul_f32_e32 v21, v25, v25
	v_fmac_f32_e32 v21, v24, v24
	v_add_f32_e32 v20, v21, v20
	v_add_f32_e32 v20, v34, v20
	ds_swizzle_b32 v21, v20 offset:swizzle(SWAP,16)
	v_cvt_pk_bf16_f32 v17, v22, v23
	v_cvt_pk_bf16_f32 v18, v18, v19
	v_cvt_pk_bf16_f32 v19, v24, v25
	v_or_b32_e32 v22, 0x100, v33
	global_store_dwordx4 v22, v[16:19], s[86:87]
	s_waitcnt lgkmcnt(0)
	s_nop 0
	v_add_f32_e32 v16, v20, v21
	v_mov_b32_e32 v17, v16
	s_nop 1
	v_permlane32_swap_b32_e32 v16, v17
	s_and_saveexec_b64 s[28:29], s[36:37]
	s_cbranch_execz .LBB0_700
	s_lshl_b32 s2, s18, 4
	s_or_b32 s2, s2, s64
	v_lshl_add_u32 v18, v32, 6, s2
	v_add_f32_e32 v16, v16, v17
	global_store_dword v18, v16, s[92:93]
.LBB0_700:
	s_or_b64 exec, exec, s[28:29]
	v_lshlrev_b32_e32 v18, 16, v232
	v_and_b32_e32 v19, 0xffff0000, v232
	v_lshlrev_b32_e32 v20, 16, v233
	v_and_b32_e32 v21, 0xffff0000, v233
	v_lshlrev_b32_e32 v22, 16, v234
	v_and_b32_e32 v23, 0xffff0000, v234
	v_lshlrev_b32_e32 v24, 16, v235
	v_and_b32_e32 v25, 0xffff0000, v235
	v_add_u32_e32 v16, 0xb0, v169
	v_pk_fma_f32 v[14:15], s[44:45], v[14:15], v[20:21]
	v_pk_fma_f32 v[12:13], s[16:17], v[12:13], v[18:19]
	v_pk_fma_f32 v[18:19], s[44:45], v[10:11], v[24:25]
	v_pk_fma_f32 v[20:21], s[16:17], v[8:9], v[22:23]
	v_lshl_add_u32 v17, v16, 11, v170
	v_cvt_pk_bf16_f32 v8, v12, v13
	v_cvt_pk_bf16_f32 v9, v14, v15
	v_cvt_pk_bf16_f32 v10, v20, v21
	v_cvt_pk_bf16_f32 v11, v18, v19
	global_store_dwordx4 v17, v[8:11], s[86:87]
	s_nop 1
	v_mul_f32_e32 v8, v13, v13
	v_mul_f32_e32 v9, v15, v15
	v_fmac_f32_e32 v8, v12, v12
	v_fmac_f32_e32 v9, v14, v14
	v_add_f32_e32 v8, v8, v9
	v_mul_f32_e32 v9, v21, v21
	v_fmac_f32_e32 v9, v20, v20
	v_add_f32_e32 v8, v9, v8
	v_mul_f32_e32 v9, v19, v19
	v_fmac_f32_e32 v9, v18, v18
	v_add_f32_e32 v18, v9, v8
	v_lshlrev_b32_e32 v8, 16, v236
	v_and_b32_e32 v9, 0xffff0000, v236
	v_lshlrev_b32_e32 v10, 16, v237
	v_and_b32_e32 v11, 0xffff0000, v237
	v_lshlrev_b32_e32 v12, 16, v238
	v_and_b32_e32 v13, 0xffff0000, v238
	v_lshlrev_b32_e32 v14, 16, v239
	v_and_b32_e32 v15, 0xffff0000, v239
	v_pk_fma_f32 v[4:5], s[16:17], v[4:5], v[8:9]
	v_pk_fma_f32 v[6:7], s[44:45], v[6:7], v[10:11]
	v_pk_fma_f32 v[8:9], s[44:45], v[2:3], v[14:15]
	v_pk_fma_f32 v[2:3], s[16:17], v[0:1], v[12:13]
	v_cvt_pk_bf16_f32 v0, v4, v5
	v_mul_f32_e32 v5, v5, v5
	v_fmac_f32_e32 v5, v4, v4
	v_mul_f32_e32 v4, v7, v7
	v_fmac_f32_e32 v4, v6, v6
	v_add_f32_e32 v4, v5, v4
	v_mul_f32_e32 v5, v3, v3
	v_fmac_f32_e32 v5, v2, v2
	v_add_f32_e32 v4, v5, v4
	v_mul_f32_e32 v5, v9, v9
	v_fmac_f32_e32 v5, v8, v8
	v_add_f32_e32 v4, v5, v4
	v_add_f32_e32 v4, v18, v4
	ds_swizzle_b32 v5, v4 offset:swizzle(SWAP,16)
	v_cvt_pk_bf16_f32 v1, v6, v7
	v_cvt_pk_bf16_f32 v2, v2, v3
	v_cvt_pk_bf16_f32 v3, v8, v9
	v_or_b32_e32 v6, 0x100, v17
	global_store_dwordx4 v6, v[0:3], s[86:87]
	s_waitcnt lgkmcnt(0)
	s_nop 0
	v_add_f32_e32 v0, v4, v5
	v_mov_b32_e32 v1, v0
	s_nop 1
	v_permlane32_swap_b32_e32 v0, v1
	s_and_saveexec_b64 s[28:29], s[36:37]
	s_cbranch_execz .LBB0_702
	s_lshl_b32 s2, s18, 4
	s_or_b32 s2, s2, s64
	v_lshl_add_u32 v2, v16, 6, s2
	v_add_f32_e32 v0, v0, v1
	global_store_dword v2, v0, s[92:93]
